# ConvFFN epilogue fast path also covers the first tile of each sequence (rows before the sequence start zeroed explicitly, sign-extended store base)
# speedup vs baseline: 1.2493x; 1.0034x over previous
.Lgm_p7_loop:
	ds_read_b128 v[216:219], v132 offset:16384
	ds_read_b128 v[200:203], v133
	ds_read_b128 v[220:223], v132 offset:18432
	ds_read_b128 v[224:227], v132 offset:20480
	ds_read_b128 v[228:231], v132 offset:22528
	ds_read_b128 v[204:207], v133 offset:2048
	ds_read_b128 v[208:211], v133 offset:4096
	ds_read_b128 v[212:215], v133 offset:6144
	s_setprio 1
	s_waitcnt lgkmcnt(3)
	v_mfma_f32_16x16x32_bf16 v[0:3], v[216:219], v[200:203], v[0:3]
	ds_read_b128 v[138:141], v130 offset:16384
	v_mfma_f32_16x16x32_bf16 v[4:7], v[220:223], v[200:203], v[4:7]
	ds_read_b128 v[232:235], v131
	v_mfma_f32_16x16x32_bf16 v[8:11], v[224:227], v[200:203], v[8:11]
	ds_read_b128 v[142:145], v130 offset:18432
	v_mfma_f32_16x16x32_bf16 v[12:15], v[228:231], v[200:203], v[12:15]
	ds_read_b128 v[146:149], v130 offset:20480
	s_waitcnt lgkmcnt(4)
	v_mfma_f32_16x16x32_bf16 v[16:19], v[216:219], v[204:207], v[16:19]
	ds_read_b128 v[150:153], v130 offset:22528
	v_mfma_f32_16x16x32_bf16 v[20:23], v[220:223], v[204:207], v[20:23]
	ds_read_b128 v[236:239], v131 offset:2048
	v_mfma_f32_16x16x32_bf16 v[24:27], v[224:227], v[204:207], v[24:27]
	ds_read_b128 v[240:243], v131 offset:4096
	v_mfma_f32_16x16x32_bf16 v[28:31], v[228:231], v[204:207], v[28:31]
	ds_read_b128 v[244:247], v131 offset:6144
	v_mfma_f32_16x16x32_bf16 v[32:35], v[216:219], v[208:211], v[32:35]
	s_waitcnt vmcnt(8)
	ds_write_b128 v166, v[168:171] offset:32768
	v_mfma_f32_16x16x32_bf16 v[36:39], v[220:223], v[208:211], v[36:39]
	ds_write_b128 v166, v[184:187] offset:49152
	v_mfma_f32_16x16x32_bf16 v[40:43], v[224:227], v[208:211], v[40:43]
	ds_write_b128 v166, v[172:175] offset:36864
	v_mfma_f32_16x16x32_bf16 v[44:47], v[228:231], v[208:211], v[44:47]
	ds_write_b128 v166, v[188:191] offset:53248
	v_mfma_f32_16x16x32_bf16 v[48:51], v[216:219], v[212:215], v[48:51]
	ds_write_b128 v166, v[176:179] offset:40960
	v_mfma_f32_16x16x32_bf16 v[52:55], v[220:223], v[212:215], v[52:55]
	ds_write_b128 v166, v[192:195] offset:57344
	v_mfma_f32_16x16x32_bf16 v[56:59], v[224:227], v[212:215], v[56:59]
	ds_write_b128 v166, v[180:183] offset:45056
	v_mfma_f32_16x16x32_bf16 v[60:63], v[228:231], v[212:215], v[60:63]
	s_waitcnt lgkmcnt(8)
	ds_write_b128 v166, v[196:199] offset:61440
	v_mfma_f32_16x16x32_bf16 v[0:3], v[138:141], v[232:235], v[0:3]
	v_mfma_f32_16x16x32_bf16 v[4:7], v[142:145], v[232:235], v[4:7]
	v_mfma_f32_16x16x32_bf16 v[8:11], v[146:149], v[232:235], v[8:11]
	v_mfma_f32_16x16x32_bf16 v[12:15], v[150:153], v[232:235], v[12:15]
	s_waitcnt lgkmcnt(8)
	v_mfma_f32_16x16x32_bf16 v[16:19], v[138:141], v[236:239], v[16:19]
	s_waitcnt lgkmcnt(0)
	global_load_dwordx4 v[168:171], v126, s[64:65] offset:384
	v_mfma_f32_16x16x32_bf16 v[20:23], v[142:145], v[236:239], v[20:23]
	global_load_dwordx4 v[184:187], v128, s[66:67] offset:384
	v_mfma_f32_16x16x32_bf16 v[24:27], v[146:149], v[236:239], v[24:27]
	global_load_dwordx4 v[172:175], v127, s[64:65] offset:384
	v_mfma_f32_16x16x32_bf16 v[28:31], v[150:153], v[236:239], v[28:31]
	global_load_dwordx4 v[188:191], v129, s[66:67] offset:384
	v_mfma_f32_16x16x32_bf16 v[32:35], v[138:141], v[240:243], v[32:35]
	global_load_dwordx4 v[176:179], v137, s[64:65] offset:384
	v_mfma_f32_16x16x32_bf16 v[36:39], v[142:145], v[240:243], v[36:39]
	global_load_dwordx4 v[192:195], v161, s[66:67] offset:384
	v_mfma_f32_16x16x32_bf16 v[40:43], v[146:149], v[240:243], v[40:43]
	global_load_dwordx4 v[180:183], v117, s[64:65] offset:384
	v_mfma_f32_16x16x32_bf16 v[44:47], v[150:153], v[240:243], v[44:47]
	global_load_dwordx4 v[196:199], v162, s[66:67] offset:384
	v_mfma_f32_16x16x32_bf16 v[48:51], v[138:141], v[244:247], v[48:51]
	v_mfma_f32_16x16x32_bf16 v[52:55], v[142:145], v[244:247], v[52:55]
	v_mfma_f32_16x16x32_bf16 v[56:59], v[146:149], v[244:247], v[56:59]
	v_mfma_f32_16x16x32_bf16 v[60:63], v[150:153], v[244:247], v[60:63]
	s_setprio 0
	s_barrier
	ds_read_b128 v[216:219], v132 offset:49152
	ds_read_b128 v[200:203], v133 offset:32768
	ds_read_b128 v[220:223], v132 offset:51200
	ds_read_b128 v[224:227], v132 offset:53248
	ds_read_b128 v[228:231], v132 offset:55296
	ds_read_b128 v[204:207], v133 offset:34816
	ds_read_b128 v[208:211], v133 offset:36864
	ds_read_b128 v[212:215], v133 offset:38912
	s_setprio 1
	s_waitcnt lgkmcnt(3)
	v_mfma_f32_16x16x32_bf16 v[0:3], v[216:219], v[200:203], v[0:3]
	ds_read_b128 v[138:141], v130 offset:49152
	v_mfma_f32_16x16x32_bf16 v[4:7], v[220:223], v[200:203], v[4:7]
	ds_read_b128 v[232:235], v131 offset:32768
	v_mfma_f32_16x16x32_bf16 v[8:11], v[224:227], v[200:203], v[8:11]
	ds_read_b128 v[142:145], v130 offset:51200
	v_mfma_f32_16x16x32_bf16 v[12:15], v[228:231], v[200:203], v[12:15]
	ds_read_b128 v[146:149], v130 offset:53248
	s_waitcnt lgkmcnt(4)
	v_mfma_f32_16x16x32_bf16 v[16:19], v[216:219], v[204:207], v[16:19]
	ds_read_b128 v[150:153], v130 offset:55296
	v_mfma_f32_16x16x32_bf16 v[20:23], v[220:223], v[204:207], v[20:23]
	ds_read_b128 v[236:239], v131 offset:34816
	v_mfma_f32_16x16x32_bf16 v[24:27], v[224:227], v[204:207], v[24:27]
	ds_read_b128 v[240:243], v131 offset:36864
	v_mfma_f32_16x16x32_bf16 v[28:31], v[228:231], v[204:207], v[28:31]
	ds_read_b128 v[244:247], v131 offset:38912
	v_mfma_f32_16x16x32_bf16 v[32:35], v[216:219], v[208:211], v[32:35]
	s_waitcnt vmcnt(8)
	ds_write_b128 v166, v[64:67]
	v_mfma_f32_16x16x32_bf16 v[36:39], v[220:223], v[208:211], v[36:39]
	ds_write_b128 v166, v[80:83] offset:16384
	v_mfma_f32_16x16x32_bf16 v[40:43], v[224:227], v[208:211], v[40:43]
	ds_write_b128 v166, v[68:71] offset:4096
	v_mfma_f32_16x16x32_bf16 v[44:47], v[228:231], v[208:211], v[44:47]
	ds_write_b128 v166, v[84:87] offset:20480
	v_mfma_f32_16x16x32_bf16 v[48:51], v[216:219], v[212:215], v[48:51]
	ds_write_b128 v166, v[72:75] offset:8192
	v_mfma_f32_16x16x32_bf16 v[52:55], v[220:223], v[212:215], v[52:55]
	ds_write_b128 v166, v[88:91] offset:24576
	v_mfma_f32_16x16x32_bf16 v[56:59], v[224:227], v[212:215], v[56:59]
	ds_write_b128 v166, v[76:79] offset:12288
	v_mfma_f32_16x16x32_bf16 v[60:63], v[228:231], v[212:215], v[60:63]
	s_waitcnt lgkmcnt(8)
	ds_write_b128 v166, v[92:95] offset:28672
	v_mfma_f32_16x16x32_bf16 v[0:3], v[138:141], v[232:235], v[0:3]
	v_mfma_f32_16x16x32_bf16 v[4:7], v[142:145], v[232:235], v[4:7]
	v_mfma_f32_16x16x32_bf16 v[8:11], v[146:149], v[232:235], v[8:11]
	v_mfma_f32_16x16x32_bf16 v[12:15], v[150:153], v[232:235], v[12:15]
	s_waitcnt lgkmcnt(8)
	v_mfma_f32_16x16x32_bf16 v[16:19], v[138:141], v[236:239], v[16:19]
	s_waitcnt lgkmcnt(0)
	global_load_dwordx4 v[64:67], v126, s[64:65] offset:512
	v_mfma_f32_16x16x32_bf16 v[20:23], v[142:145], v[236:239], v[20:23]
	global_load_dwordx4 v[80:83], v128, s[66:67] offset:512
	v_mfma_f32_16x16x32_bf16 v[24:27], v[146:149], v[236:239], v[24:27]
	global_load_dwordx4 v[68:71], v127, s[64:65] offset:512
	v_mfma_f32_16x16x32_bf16 v[28:31], v[150:153], v[236:239], v[28:31]
	global_load_dwordx4 v[84:87], v129, s[66:67] offset:512
	v_mfma_f32_16x16x32_bf16 v[32:35], v[138:141], v[240:243], v[32:35]
	global_load_dwordx4 v[72:75], v137, s[64:65] offset:512
	v_mfma_f32_16x16x32_bf16 v[36:39], v[142:145], v[240:243], v[36:39]
	global_load_dwordx4 v[88:91], v161, s[66:67] offset:512
	v_mfma_f32_16x16x32_bf16 v[40:43], v[146:149], v[240:243], v[40:43]
	global_load_dwordx4 v[76:79], v117, s[64:65] offset:512
	v_mfma_f32_16x16x32_bf16 v[44:47], v[150:153], v[240:243], v[44:47]
	global_load_dwordx4 v[92:95], v162, s[66:67] offset:512
	v_mfma_f32_16x16x32_bf16 v[48:51], v[138:141], v[244:247], v[48:51]
	v_mfma_f32_16x16x32_bf16 v[52:55], v[142:145], v[244:247], v[52:55]
	v_mfma_f32_16x16x32_bf16 v[56:59], v[146:149], v[244:247], v[56:59]
	v_mfma_f32_16x16x32_bf16 v[60:63], v[150:153], v[244:247], v[60:63]
	s_setprio 0
	s_barrier
	s_add_u32 s64, s64, 0x100
	s_addc_u32 s65, s65, 0
	s_add_u32 s66, s66, 0x100
	s_addc_u32 s67, s67, 0
	s_sub_u32 s68, s68, 1
	s_cmp_lg_u32 s68, 0
	s_cbranch_scc1 .Lgm_p7_loop
	ds_read_b128 v[216:219], v132 offset:16384
	ds_read_b128 v[200:203], v133
	ds_read_b128 v[220:223], v132 offset:18432
	ds_read_b128 v[224:227], v132 offset:20480
	ds_read_b128 v[228:231], v132 offset:22528
	ds_read_b128 v[204:207], v133 offset:2048
	ds_read_b128 v[208:211], v133 offset:4096
	ds_read_b128 v[212:215], v133 offset:6144
	s_setprio 1
	s_waitcnt lgkmcnt(3)
	v_mfma_f32_16x16x32_bf16 v[0:3], v[216:219], v[200:203], v[0:3]
	ds_read_b128 v[138:141], v130 offset:16384
	v_mfma_f32_16x16x32_bf16 v[4:7], v[220:223], v[200:203], v[4:7]
	ds_read_b128 v[232:235], v131
	v_mfma_f32_16x16x32_bf16 v[8:11], v[224:227], v[200:203], v[8:11]
	ds_read_b128 v[142:145], v130 offset:18432
	v_mfma_f32_16x16x32_bf16 v[12:15], v[228:231], v[200:203], v[12:15]
	ds_read_b128 v[146:149], v130 offset:20480
	s_waitcnt lgkmcnt(4)
	v_mfma_f32_16x16x32_bf16 v[16:19], v[216:219], v[204:207], v[16:19]
	ds_read_b128 v[150:153], v130 offset:22528
	v_mfma_f32_16x16x32_bf16 v[20:23], v[220:223], v[204:207], v[20:23]
	ds_read_b128 v[236:239], v131 offset:2048
	v_mfma_f32_16x16x32_bf16 v[24:27], v[224:227], v[204:207], v[24:27]
	ds_read_b128 v[240:243], v131 offset:4096
	v_mfma_f32_16x16x32_bf16 v[28:31], v[228:231], v[204:207], v[28:31]
	ds_read_b128 v[244:247], v131 offset:6144
	v_mfma_f32_16x16x32_bf16 v[32:35], v[216:219], v[208:211], v[32:35]
	s_waitcnt vmcnt(8)
	ds_write_b128 v166, v[168:171] offset:32768
	v_mfma_f32_16x16x32_bf16 v[36:39], v[220:223], v[208:211], v[36:39]
	ds_write_b128 v166, v[184:187] offset:49152
	v_mfma_f32_16x16x32_bf16 v[40:43], v[224:227], v[208:211], v[40:43]
	ds_write_b128 v166, v[172:175] offset:36864
	v_mfma_f32_16x16x32_bf16 v[44:47], v[228:231], v[208:211], v[44:47]
	ds_write_b128 v166, v[188:191] offset:53248
	v_mfma_f32_16x16x32_bf16 v[48:51], v[216:219], v[212:215], v[48:51]
	ds_write_b128 v166, v[176:179] offset:40960
	v_mfma_f32_16x16x32_bf16 v[52:55], v[220:223], v[212:215], v[52:55]
	ds_write_b128 v166, v[192:195] offset:57344
	v_mfma_f32_16x16x32_bf16 v[56:59], v[224:227], v[212:215], v[56:59]
	ds_write_b128 v166, v[180:183] offset:45056
	v_mfma_f32_16x16x32_bf16 v[60:63], v[228:231], v[212:215], v[60:63]
	s_waitcnt lgkmcnt(8)
	ds_write_b128 v166, v[196:199] offset:61440
	v_mfma_f32_16x16x32_bf16 v[0:3], v[138:141], v[232:235], v[0:3]
	v_mfma_f32_16x16x32_bf16 v[4:7], v[142:145], v[232:235], v[4:7]
	v_mfma_f32_16x16x32_bf16 v[8:11], v[146:149], v[232:235], v[8:11]
	v_mfma_f32_16x16x32_bf16 v[12:15], v[150:153], v[232:235], v[12:15]
	s_waitcnt lgkmcnt(8)
	v_mfma_f32_16x16x32_bf16 v[16:19], v[138:141], v[236:239], v[16:19]
	s_waitcnt lgkmcnt(0)
	global_load_dwordx4 v[168:171], v126, s[64:65] offset:384
	v_mfma_f32_16x16x32_bf16 v[20:23], v[142:145], v[236:239], v[20:23]
	global_load_dwordx4 v[184:187], v128, s[66:67] offset:384
	v_mfma_f32_16x16x32_bf16 v[24:27], v[146:149], v[236:239], v[24:27]
	global_load_dwordx4 v[172:175], v127, s[64:65] offset:384
	v_mfma_f32_16x16x32_bf16 v[28:31], v[150:153], v[236:239], v[28:31]
	global_load_dwordx4 v[188:191], v129, s[66:67] offset:384
	v_mfma_f32_16x16x32_bf16 v[32:35], v[138:141], v[240:243], v[32:35]
	global_load_dwordx4 v[176:179], v137, s[64:65] offset:384
	v_mfma_f32_16x16x32_bf16 v[36:39], v[142:145], v[240:243], v[36:39]
	global_load_dwordx4 v[192:195], v161, s[66:67] offset:384
	v_mfma_f32_16x16x32_bf16 v[40:43], v[146:149], v[240:243], v[40:43]
	global_load_dwordx4 v[180:183], v117, s[64:65] offset:384
	v_mfma_f32_16x16x32_bf16 v[44:47], v[150:153], v[240:243], v[44:47]
	global_load_dwordx4 v[196:199], v162, s[66:67] offset:384
	v_mfma_f32_16x16x32_bf16 v[48:51], v[138:141], v[244:247], v[48:51]
	v_mfma_f32_16x16x32_bf16 v[52:55], v[142:145], v[244:247], v[52:55]
	v_mfma_f32_16x16x32_bf16 v[56:59], v[146:149], v[244:247], v[56:59]
	v_mfma_f32_16x16x32_bf16 v[60:63], v[150:153], v[244:247], v[60:63]
	s_setprio 0
	s_barrier
	ds_read_b128 v[216:219], v132 offset:49152
	ds_read_b128 v[200:203], v133 offset:32768
	ds_read_b128 v[220:223], v132 offset:51200
	ds_read_b128 v[224:227], v132 offset:53248
	ds_read_b128 v[228:231], v132 offset:55296
	ds_read_b128 v[204:207], v133 offset:34816
	ds_read_b128 v[208:211], v133 offset:36864
	ds_read_b128 v[212:215], v133 offset:38912
	s_setprio 1
	s_waitcnt lgkmcnt(3)
	v_mfma_f32_16x16x32_bf16 v[0:3], v[216:219], v[200:203], v[0:3]
	ds_read_b128 v[138:141], v130 offset:49152
	v_mfma_f32_16x16x32_bf16 v[4:7], v[220:223], v[200:203], v[4:7]
	ds_read_b128 v[232:235], v131 offset:32768
	v_mfma_f32_16x16x32_bf16 v[8:11], v[224:227], v[200:203], v[8:11]
	ds_read_b128 v[142:145], v130 offset:51200
	v_mfma_f32_16x16x32_bf16 v[12:15], v[228:231], v[200:203], v[12:15]
	ds_read_b128 v[146:149], v130 offset:53248
	s_waitcnt lgkmcnt(4)
	v_mfma_f32_16x16x32_bf16 v[16:19], v[216:219], v[204:207], v[16:19]
	ds_read_b128 v[150:153], v130 offset:55296
	v_mfma_f32_16x16x32_bf16 v[20:23], v[220:223], v[204:207], v[20:23]
	ds_read_b128 v[236:239], v131 offset:34816
	v_mfma_f32_16x16x32_bf16 v[24:27], v[224:227], v[204:207], v[24:27]
	ds_read_b128 v[240:243], v131 offset:36864
	v_mfma_f32_16x16x32_bf16 v[28:31], v[228:231], v[204:207], v[28:31]
	ds_read_b128 v[244:247], v131 offset:38912
	v_mfma_f32_16x16x32_bf16 v[32:35], v[216:219], v[208:211], v[32:35]
	s_waitcnt vmcnt(8)
	ds_write_b128 v166, v[64:67]
	v_mfma_f32_16x16x32_bf16 v[36:39], v[220:223], v[208:211], v[36:39]
	ds_write_b128 v166, v[80:83] offset:16384
	v_mfma_f32_16x16x32_bf16 v[40:43], v[224:227], v[208:211], v[40:43]
	ds_write_b128 v166, v[68:71] offset:4096
	v_mfma_f32_16x16x32_bf16 v[44:47], v[228:231], v[208:211], v[44:47]
	ds_write_b128 v166, v[84:87] offset:20480
	v_mfma_f32_16x16x32_bf16 v[48:51], v[216:219], v[212:215], v[48:51]
	ds_write_b128 v166, v[72:75] offset:8192
	v_mfma_f32_16x16x32_bf16 v[52:55], v[220:223], v[212:215], v[52:55]
	ds_write_b128 v166, v[88:91] offset:24576
	v_mfma_f32_16x16x32_bf16 v[56:59], v[224:227], v[212:215], v[56:59]
	ds_write_b128 v166, v[76:79] offset:12288
	v_mfma_f32_16x16x32_bf16 v[60:63], v[228:231], v[212:215], v[60:63]
	s_waitcnt lgkmcnt(8)
	ds_write_b128 v166, v[92:95] offset:28672
	v_mfma_f32_16x16x32_bf16 v[0:3], v[138:141], v[232:235], v[0:3]
	v_mfma_f32_16x16x32_bf16 v[4:7], v[142:145], v[232:235], v[4:7]
	v_mfma_f32_16x16x32_bf16 v[8:11], v[146:149], v[232:235], v[8:11]
	v_mfma_f32_16x16x32_bf16 v[12:15], v[150:153], v[232:235], v[12:15]
	s_waitcnt lgkmcnt(8)
	v_mfma_f32_16x16x32_bf16 v[16:19], v[138:141], v[236:239], v[16:19]
	v_mfma_f32_16x16x32_bf16 v[20:23], v[142:145], v[236:239], v[20:23]
	v_mfma_f32_16x16x32_bf16 v[24:27], v[146:149], v[236:239], v[24:27]
	v_mfma_f32_16x16x32_bf16 v[28:31], v[150:153], v[236:239], v[28:31]
	v_mfma_f32_16x16x32_bf16 v[32:35], v[138:141], v[240:243], v[32:35]
	v_mfma_f32_16x16x32_bf16 v[36:39], v[142:145], v[240:243], v[36:39]
	v_mfma_f32_16x16x32_bf16 v[40:43], v[146:149], v[240:243], v[40:43]
	v_mfma_f32_16x16x32_bf16 v[44:47], v[150:153], v[240:243], v[44:47]
	v_mfma_f32_16x16x32_bf16 v[48:51], v[138:141], v[244:247], v[48:51]
	v_mfma_f32_16x16x32_bf16 v[52:55], v[142:145], v[244:247], v[52:55]
	v_mfma_f32_16x16x32_bf16 v[56:59], v[146:149], v[244:247], v[56:59]
	v_mfma_f32_16x16x32_bf16 v[60:63], v[150:153], v[244:247], v[60:63]
	s_setprio 0
	s_waitcnt lgkmcnt(0)
	s_barrier
	ds_read_b128 v[216:219], v132 offset:16384
	ds_read_b128 v[200:203], v133
	ds_read_b128 v[220:223], v132 offset:18432
	ds_read_b128 v[224:227], v132 offset:20480
	ds_read_b128 v[228:231], v132 offset:22528
	ds_read_b128 v[204:207], v133 offset:2048
	ds_read_b128 v[208:211], v133 offset:4096
	ds_read_b128 v[212:215], v133 offset:6144
	s_setprio 1
	s_waitcnt lgkmcnt(3)
	v_mfma_f32_16x16x32_bf16 v[0:3], v[216:219], v[200:203], v[0:3]
	ds_read_b128 v[138:141], v130 offset:16384
	v_mfma_f32_16x16x32_bf16 v[4:7], v[220:223], v[200:203], v[4:7]
	ds_read_b128 v[232:235], v131
	v_mfma_f32_16x16x32_bf16 v[8:11], v[224:227], v[200:203], v[8:11]
	ds_read_b128 v[142:145], v130 offset:18432
	v_mfma_f32_16x16x32_bf16 v[12:15], v[228:231], v[200:203], v[12:15]
	ds_read_b128 v[146:149], v130 offset:20480
	s_waitcnt lgkmcnt(4)
	v_mfma_f32_16x16x32_bf16 v[16:19], v[216:219], v[204:207], v[16:19]
	ds_read_b128 v[150:153], v130 offset:22528
	v_mfma_f32_16x16x32_bf16 v[20:23], v[220:223], v[204:207], v[20:23]
	ds_read_b128 v[236:239], v131 offset:2048
	v_mfma_f32_16x16x32_bf16 v[24:27], v[224:227], v[204:207], v[24:27]
	ds_read_b128 v[240:243], v131 offset:4096
	v_mfma_f32_16x16x32_bf16 v[28:31], v[228:231], v[204:207], v[28:31]
	ds_read_b128 v[244:247], v131 offset:6144
	v_mfma_f32_16x16x32_bf16 v[32:35], v[216:219], v[208:211], v[32:35]
	s_waitcnt vmcnt(0)
	ds_write_b128 v166, v[168:171] offset:32768
	v_mfma_f32_16x16x32_bf16 v[36:39], v[220:223], v[208:211], v[36:39]
	ds_write_b128 v166, v[184:187] offset:49152
	v_mfma_f32_16x16x32_bf16 v[40:43], v[224:227], v[208:211], v[40:43]
	ds_write_b128 v166, v[172:175] offset:36864
	v_mfma_f32_16x16x32_bf16 v[44:47], v[228:231], v[208:211], v[44:47]
	ds_write_b128 v166, v[188:191] offset:53248
	v_mfma_f32_16x16x32_bf16 v[48:51], v[216:219], v[212:215], v[48:51]
	ds_write_b128 v166, v[176:179] offset:40960
	v_mfma_f32_16x16x32_bf16 v[52:55], v[220:223], v[212:215], v[52:55]
	ds_write_b128 v166, v[192:195] offset:57344
	v_mfma_f32_16x16x32_bf16 v[56:59], v[224:227], v[212:215], v[56:59]
	ds_write_b128 v166, v[180:183] offset:45056
	v_mfma_f32_16x16x32_bf16 v[60:63], v[228:231], v[212:215], v[60:63]
	s_waitcnt lgkmcnt(8)
	ds_write_b128 v166, v[196:199] offset:61440
	v_mfma_f32_16x16x32_bf16 v[0:3], v[138:141], v[232:235], v[0:3]
	v_mfma_f32_16x16x32_bf16 v[4:7], v[142:145], v[232:235], v[4:7]
	v_mfma_f32_16x16x32_bf16 v[8:11], v[146:149], v[232:235], v[8:11]
	v_mfma_f32_16x16x32_bf16 v[12:15], v[150:153], v[232:235], v[12:15]
	s_waitcnt lgkmcnt(8)
	v_mfma_f32_16x16x32_bf16 v[16:19], v[138:141], v[236:239], v[16:19]
	v_mfma_f32_16x16x32_bf16 v[20:23], v[142:145], v[236:239], v[20:23]
	v_mfma_f32_16x16x32_bf16 v[24:27], v[146:149], v[236:239], v[24:27]
	v_mfma_f32_16x16x32_bf16 v[28:31], v[150:153], v[236:239], v[28:31]
	v_mfma_f32_16x16x32_bf16 v[32:35], v[138:141], v[240:243], v[32:35]
	v_mfma_f32_16x16x32_bf16 v[36:39], v[142:145], v[240:243], v[36:39]
	v_mfma_f32_16x16x32_bf16 v[40:43], v[146:149], v[240:243], v[40:43]
	v_mfma_f32_16x16x32_bf16 v[44:47], v[150:153], v[240:243], v[44:47]
	v_mfma_f32_16x16x32_bf16 v[48:51], v[138:141], v[244:247], v[48:51]
	v_mfma_f32_16x16x32_bf16 v[52:55], v[142:145], v[244:247], v[52:55]
	v_mfma_f32_16x16x32_bf16 v[56:59], v[146:149], v[244:247], v[56:59]
	v_mfma_f32_16x16x32_bf16 v[60:63], v[150:153], v[244:247], v[60:63]
	s_setprio 0
	s_waitcnt lgkmcnt(0)
	s_barrier
	ds_read_b128 v[216:219], v132 offset:49152
	ds_read_b128 v[200:203], v133 offset:32768
	ds_read_b128 v[220:223], v132 offset:51200
	ds_read_b128 v[224:227], v132 offset:53248
	ds_read_b128 v[228:231], v132 offset:55296
	ds_read_b128 v[204:207], v133 offset:34816
	ds_read_b128 v[208:211], v133 offset:36864
	ds_read_b128 v[212:215], v133 offset:38912
	s_setprio 1
	s_waitcnt lgkmcnt(3)
	v_mfma_f32_16x16x32_bf16 v[0:3], v[216:219], v[200:203], v[0:3]
	ds_read_b128 v[138:141], v130 offset:49152
	v_mfma_f32_16x16x32_bf16 v[4:7], v[220:223], v[200:203], v[4:7]
	ds_read_b128 v[232:235], v131 offset:32768
	v_mfma_f32_16x16x32_bf16 v[8:11], v[224:227], v[200:203], v[8:11]
	ds_read_b128 v[142:145], v130 offset:51200
	v_mfma_f32_16x16x32_bf16 v[12:15], v[228:231], v[200:203], v[12:15]
	ds_read_b128 v[146:149], v130 offset:53248
	s_waitcnt lgkmcnt(4)
	v_mfma_f32_16x16x32_bf16 v[16:19], v[216:219], v[204:207], v[16:19]
	ds_read_b128 v[150:153], v130 offset:55296
	v_mfma_f32_16x16x32_bf16 v[20:23], v[220:223], v[204:207], v[20:23]
	ds_read_b128 v[236:239], v131 offset:34816
	v_mfma_f32_16x16x32_bf16 v[24:27], v[224:227], v[204:207], v[24:27]
	ds_read_b128 v[240:243], v131 offset:36864
	v_mfma_f32_16x16x32_bf16 v[28:31], v[228:231], v[204:207], v[28:31]
	ds_read_b128 v[244:247], v131 offset:38912
	v_mfma_f32_16x16x32_bf16 v[32:35], v[216:219], v[208:211], v[32:35]
	v_mfma_f32_16x16x32_bf16 v[36:39], v[220:223], v[208:211], v[36:39]
	v_mfma_f32_16x16x32_bf16 v[40:43], v[224:227], v[208:211], v[40:43]
	v_mfma_f32_16x16x32_bf16 v[44:47], v[228:231], v[208:211], v[44:47]
	v_mfma_f32_16x16x32_bf16 v[48:51], v[216:219], v[212:215], v[48:51]
	v_mfma_f32_16x16x32_bf16 v[52:55], v[220:223], v[212:215], v[52:55]
	v_mfma_f32_16x16x32_bf16 v[56:59], v[224:227], v[212:215], v[56:59]
	v_mfma_f32_16x16x32_bf16 v[60:63], v[228:231], v[212:215], v[60:63]
	s_waitcnt lgkmcnt(3)
	v_mfma_f32_16x16x32_bf16 v[0:3], v[138:141], v[232:235], v[0:3]
	v_mfma_f32_16x16x32_bf16 v[4:7], v[142:145], v[232:235], v[4:7]
	v_mfma_f32_16x16x32_bf16 v[8:11], v[146:149], v[232:235], v[8:11]
	v_mfma_f32_16x16x32_bf16 v[12:15], v[150:153], v[232:235], v[12:15]
	s_waitcnt lgkmcnt(0)
	v_mfma_f32_16x16x32_bf16 v[16:19], v[138:141], v[236:239], v[16:19]
	v_mfma_f32_16x16x32_bf16 v[20:23], v[142:145], v[236:239], v[20:23]
	v_mfma_f32_16x16x32_bf16 v[24:27], v[146:149], v[236:239], v[24:27]
	v_mfma_f32_16x16x32_bf16 v[28:31], v[150:153], v[236:239], v[28:31]
	v_mfma_f32_16x16x32_bf16 v[32:35], v[138:141], v[240:243], v[32:35]
	v_mfma_f32_16x16x32_bf16 v[36:39], v[142:145], v[240:243], v[36:39]
	v_mfma_f32_16x16x32_bf16 v[40:43], v[146:149], v[240:243], v[40:43]
	v_mfma_f32_16x16x32_bf16 v[44:47], v[150:153], v[240:243], v[44:47]
	v_mfma_f32_16x16x32_bf16 v[48:51], v[138:141], v[244:247], v[48:51]
	v_mfma_f32_16x16x32_bf16 v[52:55], v[142:145], v[244:247], v[52:55]
	v_mfma_f32_16x16x32_bf16 v[56:59], v[146:149], v[244:247], v[56:59]
	v_mfma_f32_16x16x32_bf16 v[60:63], v[150:153], v[244:247], v[60:63]
	s_setprio 0
	s_nop 7
	s_barrier
	ds_write_b128 v136, v[0:3]
	ds_write_b128 v136, v[4:7] offset:64
	ds_write_b128 v136, v[8:11] offset:128
	ds_write_b128 v136, v[12:15] offset:192
	ds_write_b128 v136, v[16:19] offset:8448
	ds_write_b128 v136, v[20:23] offset:8512
	ds_write_b128 v136, v[24:27] offset:8576
	ds_write_b128 v136, v[28:31] offset:8640
	ds_write_b128 v136, v[32:35] offset:16896
	ds_write_b128 v136, v[36:39] offset:16960
	ds_write_b128 v136, v[40:43] offset:17024
	ds_write_b128 v136, v[44:47] offset:17088
	ds_write_b128 v136, v[48:51] offset:25344
	ds_write_b128 v136, v[52:55] offset:25408
	ds_write_b128 v136, v[56:59] offset:25472
	ds_write_b128 v136, v[60:63] offset:25536
	v_lshl_or_b32 v20, s62, 6, v107
	v_ashrrev_i32_e32 v21, 31, v20
	v_lshlrev_b64 v[22:23], 2, v[20:21]
	v_lshl_add_u64 v[0:1], s[82:83], 0, v[22:23]
	v_lshl_add_u64 v[16:17], s[28:29], 0, v[22:23]
	v_lshl_add_u64 v[18:19], s[30:31], 0, v[22:23]
	s_waitcnt lgkmcnt(0)
	s_barrier
	v_lshl_add_u64 v[2:3], s[18:19], 0, v[22:23]
	v_lshl_add_u64 v[4:5], s[22:23], 0, v[22:23]
	v_lshl_add_u64 v[6:7], s[26:27], 0, v[22:23]
	global_load_dwordx2 v[8:9], v[0:1], off
	global_load_dwordx2 v[10:11], v[2:3], off
	global_load_dwordx2 v[12:13], v[4:5], off
	global_load_dwordx2 v[14:15], v[6:7], off
	s_nop 0
	global_load_dwordx2 v[16:17], v[16:17], off
	s_nop 0
	global_load_dwordx2 v[18:19], v[18:19], off
	s_mov_b64 s[4:5], -1
	s_and_b64 vcc, exec, s[36:37]
	s_cbranch_vccz .LBB0_852
	s_mul_i32 s65, s34, 17
	s_sub_i32 s64, s61, s65
	s_cmp_lt_i32 s64, 0
	s_cbranch_scc1 .Lp7epi_slow
	s_cmp_gt_i32 s64, 15
	s_cbranch_scc1 .Lp7epi_slow
	v_add_u32_e32 v127, 0x840, v134
	v_add_u32_e32 v128, 0x1080, v134
	v_add_u32_e32 v129, 0x18c0, v134
	s_mov_b64 s[70:71], exec
	s_and_b64 exec, exec, s[0:1]
	ds_read2_b64 v[232:235], v111 offset1:16
	ds_read2_b64 v[236:239], v113 offset1:16
	s_mov_b64 exec, s[70:71]
	ds_read2_b64 v[168:171], v134 offset0:0 offset1:16
	ds_read2_b64 v[172:175], v134 offset0:66 offset1:82
	ds_read2_b64 v[176:179], v134 offset0:132 offset1:148
	ds_read2_b64 v[180:183], v134 offset0:198 offset1:214
	ds_read2_b64 v[184:187], v127 offset0:0 offset1:16
	ds_read2_b64 v[188:191], v127 offset0:66 offset1:82
	ds_read2_b64 v[192:195], v127 offset0:132 offset1:148
	ds_read2_b64 v[196:199], v127 offset0:198 offset1:214
	ds_read2_b64 v[200:203], v128 offset0:0 offset1:16
	ds_read2_b64 v[204:207], v128 offset0:66 offset1:82
	ds_read2_b64 v[208:211], v128 offset0:132 offset1:148
	ds_read2_b64 v[212:215], v128 offset0:198 offset1:214
	ds_read2_b64 v[216:219], v129 offset0:0 offset1:16
	s_waitcnt lgkmcnt(8)
	ds_read2_b64 v[220:223], v129 offset0:66 offset1:82
	ds_read2_b64 v[224:227], v129 offset0:132 offset1:148
	ds_read2_b64 v[228:231], v129 offset0:198 offset1:214
	s_lshl_b32 s65, s34, 11
	s_mul_i32 s72, s64, 0x7e
	s_add_i32 s65, s65, s72
	s_add_i32 s65, s65, -2
	s_mul_i32 s65, s65, 0x1600
	s_ashr_i32 s72, s65, 31
	s_add_u32 s66, s80, s65
	s_addc_u32 s67, s81, s72
	v_mul_u32_u24_e32 v126, 0x1600, v105
	v_lshl_add_u32 v126, v20, 1, v126
	s_waitcnt vmcnt(0)
	s_cmp_lg_u32 s64, 0
	s_cbranch_scc1 .Lp7epi_nz
	s_waitcnt lgkmcnt(0)
	s_mov_b64 s[74:75], exec
	s_andn2_b64 exec, exec, s[0:1]
	v_mov_b32_e32 v168, 0
	v_mov_b32_e32 v169, 0
	v_mov_b32_e32 v170, 0
	v_mov_b32_e32 v171, 0
	v_mov_b32_e32 v172, 0
	v_mov_b32_e32 v173, 0
	v_mov_b32_e32 v174, 0
	v_mov_b32_e32 v175, 0
	s_mov_b64 exec, s[74:75]
.Lp7epi_nz:
	v_mul_f32_e32 v40, v8, v232
	v_mul_f32_e32 v48, v8, v236
	v_mul_f32_e32 v56, v8, v168
	v_mul_f32_e32 v64, v8, v172
	v_mul_f32_e32 v41, v9, v233
	v_mul_f32_e32 v49, v9, v237
	v_mul_f32_e32 v57, v9, v169
	v_mul_f32_e32 v65, v9, v173
	v_mul_f32_e32 v42, v14, v234
	v_mul_f32_e32 v50, v14, v238
	v_mul_f32_e32 v58, v14, v170
	v_mul_f32_e32 v66, v14, v174
	v_mul_f32_e32 v43, v15, v235
	v_mul_f32_e32 v51, v15, v239
	v_mul_f32_e32 v59, v15, v171
	v_mul_f32_e32 v67, v15, v175
	v_fma_f32 v40, v10, v236, v40
	v_fma_f32 v48, v10, v168, v48
	v_fma_f32 v56, v10, v172, v56
	v_fma_f32 v64, v10, v176, v64
	v_fma_f32 v41, v11, v237, v41
	v_fma_f32 v49, v11, v169, v49
	v_fma_f32 v57, v11, v173, v57
	v_fma_f32 v65, v11, v177, v65
	v_fma_f32 v42, v16, v238, v42
	v_fma_f32 v50, v16, v170, v50
	v_fma_f32 v58, v16, v174, v58
	v_fma_f32 v66, v16, v178, v66
	v_fma_f32 v43, v17, v239, v43
	v_fma_f32 v51, v17, v171, v51
	v_fma_f32 v59, v17, v175, v59
	v_fma_f32 v67, v17, v179, v67
	v_fma_f32 v40, v12, v168, v40
	v_fma_f32 v48, v12, v172, v48
	v_fma_f32 v56, v12, v176, v56
	v_fma_f32 v64, v12, v180, v64
	v_fma_f32 v41, v13, v169, v41
	v_fma_f32 v49, v13, v173, v49
	v_fma_f32 v57, v13, v177, v57
	v_fma_f32 v65, v13, v181, v65
	v_fma_f32 v42, v18, v170, v42
	v_fma_f32 v50, v18, v174, v50
	v_fma_f32 v58, v18, v178, v58
	v_fma_f32 v66, v18, v182, v66
	v_fma_f32 v43, v19, v171, v43
	v_fma_f32 v51, v19, v175, v51
	v_fma_f32 v59, v19, v179, v59
	v_fma_f32 v67, v19, v183, v67
	v_mul_f32_e32 v44, 0xbfb8aa3b, v40
	v_mul_f32_e32 v52, 0xbfb8aa3b, v48
	v_mul_f32_e32 v60, 0xbfb8aa3b, v56
	v_mul_f32_e32 v68, 0xbfb8aa3b, v64
	v_mul_f32_e32 v45, 0xbfb8aa3b, v41
	v_mul_f32_e32 v53, 0xbfb8aa3b, v49
	v_mul_f32_e32 v61, 0xbfb8aa3b, v57
	v_mul_f32_e32 v69, 0xbfb8aa3b, v65
	v_exp_f32_e32 v44, v44
	v_exp_f32_e32 v52, v52
	v_exp_f32_e32 v60, v60
	v_exp_f32_e32 v68, v68
	v_exp_f32_e32 v45, v45
	v_exp_f32_e32 v53, v53
	v_exp_f32_e32 v61, v61
	v_exp_f32_e32 v69, v69
	v_add_f32_e32 v44, 1.0, v44
	v_add_f32_e32 v52, 1.0, v52
	v_add_f32_e32 v60, 1.0, v60
	v_add_f32_e32 v68, 1.0, v68
	v_add_f32_e32 v45, 1.0, v45
	v_add_f32_e32 v53, 1.0, v53
	v_add_f32_e32 v61, 1.0, v61
	v_add_f32_e32 v69, 1.0, v69
	v_rcp_f32_e32 v44, v44
	v_rcp_f32_e32 v52, v52
	v_rcp_f32_e32 v60, v60
	v_rcp_f32_e32 v68, v68
	v_rcp_f32_e32 v45, v45
	v_rcp_f32_e32 v53, v53
	v_rcp_f32_e32 v61, v61
	v_rcp_f32_e32 v69, v69
	v_mul_f32_e32 v40, v40, v44
	v_mul_f32_e32 v48, v48, v52
	v_mul_f32_e32 v56, v56, v60
	v_mul_f32_e32 v64, v64, v68
	v_mul_f32_e32 v41, v41, v45
	v_mul_f32_e32 v49, v49, v53
	v_mul_f32_e32 v57, v57, v61
	v_mul_f32_e32 v65, v65, v69
	v_mul_f32_e32 v40, v42, v40
	v_mul_f32_e32 v48, v50, v48
	v_mul_f32_e32 v56, v58, v56
	v_mul_f32_e32 v64, v66, v64
	v_mul_f32_e32 v41, v43, v41
	v_mul_f32_e32 v49, v51, v49
	v_mul_f32_e32 v57, v59, v57
	v_mul_f32_e32 v65, v67, v65
	v_cvt_pk_bf16_f32 v80, v40, v41
	v_cvt_pk_bf16_f32 v81, v48, v49
	v_cvt_pk_bf16_f32 v82, v56, v57
	v_cvt_pk_bf16_f32 v83, v64, v65
	s_waitcnt lgkmcnt(10)
	s_waitcnt lgkmcnt(9)
	s_waitcnt lgkmcnt(8)
	v_mul_f32_e32 v40, v8, v176
	v_mul_f32_e32 v48, v8, v180
	v_mul_f32_e32 v56, v8, v184
	v_mul_f32_e32 v64, v8, v188
	v_mul_f32_e32 v41, v9, v177
	v_mul_f32_e32 v49, v9, v181
	v_mul_f32_e32 v57, v9, v185
	v_mul_f32_e32 v65, v9, v189
	v_mul_f32_e32 v42, v14, v178
	v_mul_f32_e32 v50, v14, v182
	v_mul_f32_e32 v58, v14, v186
	v_mul_f32_e32 v66, v14, v190
	v_mul_f32_e32 v43, v15, v179
	v_mul_f32_e32 v51, v15, v183
	v_mul_f32_e32 v59, v15, v187
	v_mul_f32_e32 v67, v15, v191
	v_fma_f32 v40, v10, v180, v40
	v_fma_f32 v48, v10, v184, v48
	v_fma_f32 v56, v10, v188, v56
	v_fma_f32 v64, v10, v192, v64
	v_fma_f32 v41, v11, v181, v41
	v_fma_f32 v49, v11, v185, v49
	v_fma_f32 v57, v11, v189, v57
	v_fma_f32 v65, v11, v193, v65
	v_fma_f32 v42, v16, v182, v42
	v_fma_f32 v50, v16, v186, v50
	v_fma_f32 v58, v16, v190, v58
	v_fma_f32 v66, v16, v194, v66
	v_fma_f32 v43, v17, v183, v43
	v_fma_f32 v51, v17, v187, v51
	v_fma_f32 v59, v17, v191, v59
	v_fma_f32 v67, v17, v195, v67
	v_fma_f32 v40, v12, v184, v40
	v_fma_f32 v48, v12, v188, v48
	v_fma_f32 v56, v12, v192, v56
	v_fma_f32 v64, v12, v196, v64
	v_fma_f32 v41, v13, v185, v41
	v_fma_f32 v49, v13, v189, v49
	v_fma_f32 v57, v13, v193, v57
	v_fma_f32 v65, v13, v197, v65
	v_fma_f32 v42, v18, v186, v42
	v_fma_f32 v50, v18, v190, v50
	v_fma_f32 v58, v18, v194, v58
	v_fma_f32 v66, v18, v198, v66
	v_fma_f32 v43, v19, v187, v43
	v_fma_f32 v51, v19, v191, v51
	v_fma_f32 v59, v19, v195, v59
	v_fma_f32 v67, v19, v199, v67
	v_mul_f32_e32 v44, 0xbfb8aa3b, v40
	v_mul_f32_e32 v52, 0xbfb8aa3b, v48
	v_mul_f32_e32 v60, 0xbfb8aa3b, v56
	v_mul_f32_e32 v68, 0xbfb8aa3b, v64
	v_mul_f32_e32 v45, 0xbfb8aa3b, v41
	v_mul_f32_e32 v53, 0xbfb8aa3b, v49
	v_mul_f32_e32 v61, 0xbfb8aa3b, v57
	v_mul_f32_e32 v69, 0xbfb8aa3b, v65
	v_exp_f32_e32 v44, v44
	v_exp_f32_e32 v52, v52
	v_exp_f32_e32 v60, v60
	v_exp_f32_e32 v68, v68
	v_exp_f32_e32 v45, v45
	v_exp_f32_e32 v53, v53
	v_exp_f32_e32 v61, v61
	v_exp_f32_e32 v69, v69
	v_add_f32_e32 v44, 1.0, v44
	v_add_f32_e32 v52, 1.0, v52
	v_add_f32_e32 v60, 1.0, v60
	v_add_f32_e32 v68, 1.0, v68
	v_add_f32_e32 v45, 1.0, v45
	v_add_f32_e32 v53, 1.0, v53
	v_add_f32_e32 v61, 1.0, v61
	v_add_f32_e32 v69, 1.0, v69
	v_rcp_f32_e32 v44, v44
	v_rcp_f32_e32 v52, v52
	v_rcp_f32_e32 v60, v60
	v_rcp_f32_e32 v68, v68
	v_rcp_f32_e32 v45, v45
	v_rcp_f32_e32 v53, v53
	v_rcp_f32_e32 v61, v61
	v_rcp_f32_e32 v69, v69
	v_mul_f32_e32 v40, v40, v44
	v_mul_f32_e32 v48, v48, v52
	v_mul_f32_e32 v56, v56, v60
	v_mul_f32_e32 v64, v64, v68
	v_mul_f32_e32 v41, v41, v45
	v_mul_f32_e32 v49, v49, v53
	v_mul_f32_e32 v57, v57, v61
	v_mul_f32_e32 v65, v65, v69
	v_mul_f32_e32 v40, v42, v40
	v_mul_f32_e32 v48, v50, v48
	v_mul_f32_e32 v56, v58, v56
	v_mul_f32_e32 v64, v66, v64
	v_mul_f32_e32 v41, v43, v41
	v_mul_f32_e32 v49, v51, v49
	v_mul_f32_e32 v57, v59, v57
	v_mul_f32_e32 v65, v67, v65
	v_cvt_pk_bf16_f32 v84, v40, v41
	v_cvt_pk_bf16_f32 v85, v48, v49
	v_cvt_pk_bf16_f32 v86, v56, v57
	v_cvt_pk_bf16_f32 v87, v64, v65
	s_waitcnt lgkmcnt(7)
	s_waitcnt lgkmcnt(6)
	s_waitcnt lgkmcnt(5)
	s_waitcnt lgkmcnt(4)
	v_mul_f32_e32 v40, v8, v192
	v_mul_f32_e32 v48, v8, v196
	v_mul_f32_e32 v56, v8, v200
	v_mul_f32_e32 v64, v8, v204
	v_mul_f32_e32 v41, v9, v193
	v_mul_f32_e32 v49, v9, v197
	v_mul_f32_e32 v57, v9, v201
	v_mul_f32_e32 v65, v9, v205
	v_mul_f32_e32 v42, v14, v194
	v_mul_f32_e32 v50, v14, v198
	v_mul_f32_e32 v58, v14, v202
	v_mul_f32_e32 v66, v14, v206
	v_mul_f32_e32 v43, v15, v195
	v_mul_f32_e32 v51, v15, v199
	v_mul_f32_e32 v59, v15, v203
	v_mul_f32_e32 v67, v15, v207
	v_fma_f32 v40, v10, v196, v40
	v_fma_f32 v48, v10, v200, v48
	v_fma_f32 v56, v10, v204, v56
	v_fma_f32 v64, v10, v208, v64
	v_fma_f32 v41, v11, v197, v41
	v_fma_f32 v49, v11, v201, v49
	v_fma_f32 v57, v11, v205, v57
	v_fma_f32 v65, v11, v209, v65
	v_fma_f32 v42, v16, v198, v42
	v_fma_f32 v50, v16, v202, v50
	v_fma_f32 v58, v16, v206, v58
	v_fma_f32 v66, v16, v210, v66
	v_fma_f32 v43, v17, v199, v43
	v_fma_f32 v51, v17, v203, v51
	v_fma_f32 v59, v17, v207, v59
	v_fma_f32 v67, v17, v211, v67
	v_fma_f32 v40, v12, v200, v40
	v_fma_f32 v48, v12, v204, v48
	v_fma_f32 v56, v12, v208, v56
	v_fma_f32 v64, v12, v212, v64
	v_fma_f32 v41, v13, v201, v41
	v_fma_f32 v49, v13, v205, v49
	v_fma_f32 v57, v13, v209, v57
	v_fma_f32 v65, v13, v213, v65
	v_fma_f32 v42, v18, v202, v42
	v_fma_f32 v50, v18, v206, v50
	v_fma_f32 v58, v18, v210, v58
	v_fma_f32 v66, v18, v214, v66
	v_fma_f32 v43, v19, v203, v43
	v_fma_f32 v51, v19, v207, v51
	v_fma_f32 v59, v19, v211, v59
	v_fma_f32 v67, v19, v215, v67
	v_mul_f32_e32 v44, 0xbfb8aa3b, v40
	v_mul_f32_e32 v52, 0xbfb8aa3b, v48
	v_mul_f32_e32 v60, 0xbfb8aa3b, v56
	v_mul_f32_e32 v68, 0xbfb8aa3b, v64
	v_mul_f32_e32 v45, 0xbfb8aa3b, v41
	v_mul_f32_e32 v53, 0xbfb8aa3b, v49
	v_mul_f32_e32 v61, 0xbfb8aa3b, v57
	v_mul_f32_e32 v69, 0xbfb8aa3b, v65
	v_exp_f32_e32 v44, v44
	v_exp_f32_e32 v52, v52
	v_exp_f32_e32 v60, v60
	v_exp_f32_e32 v68, v68
	v_exp_f32_e32 v45, v45
	v_exp_f32_e32 v53, v53
	v_exp_f32_e32 v61, v61
	v_exp_f32_e32 v69, v69
	v_add_f32_e32 v44, 1.0, v44
	v_add_f32_e32 v52, 1.0, v52
	v_add_f32_e32 v60, 1.0, v60
	v_add_f32_e32 v68, 1.0, v68
	v_add_f32_e32 v45, 1.0, v45
	v_add_f32_e32 v53, 1.0, v53
	v_add_f32_e32 v61, 1.0, v61
	v_add_f32_e32 v69, 1.0, v69
	v_rcp_f32_e32 v44, v44
	v_rcp_f32_e32 v52, v52
	v_rcp_f32_e32 v60, v60
	v_rcp_f32_e32 v68, v68
	v_rcp_f32_e32 v45, v45
	v_rcp_f32_e32 v53, v53
	v_rcp_f32_e32 v61, v61
	v_rcp_f32_e32 v69, v69
	v_mul_f32_e32 v40, v40, v44
	v_mul_f32_e32 v48, v48, v52
	v_mul_f32_e32 v56, v56, v60
	v_mul_f32_e32 v64, v64, v68
	v_mul_f32_e32 v41, v41, v45
	v_mul_f32_e32 v49, v49, v53
	v_mul_f32_e32 v57, v57, v61
	v_mul_f32_e32 v65, v65, v69
	v_mul_f32_e32 v40, v42, v40
	v_mul_f32_e32 v48, v50, v48
	v_mul_f32_e32 v56, v58, v56
	v_mul_f32_e32 v64, v66, v64
	v_mul_f32_e32 v41, v43, v41
	v_mul_f32_e32 v49, v51, v49
	v_mul_f32_e32 v57, v59, v57
	v_mul_f32_e32 v65, v67, v65
	v_cvt_pk_bf16_f32 v88, v40, v41
	v_cvt_pk_bf16_f32 v89, v48, v49
	v_cvt_pk_bf16_f32 v90, v56, v57
	v_cvt_pk_bf16_f32 v91, v64, v65
	s_waitcnt lgkmcnt(3)
	s_waitcnt lgkmcnt(2)
	s_waitcnt lgkmcnt(1)
	s_waitcnt lgkmcnt(0)
	v_mul_f32_e32 v40, v8, v208
	v_mul_f32_e32 v48, v8, v212
	v_mul_f32_e32 v56, v8, v216
	v_mul_f32_e32 v64, v8, v220
	v_mul_f32_e32 v41, v9, v209
	v_mul_f32_e32 v49, v9, v213
	v_mul_f32_e32 v57, v9, v217
	v_mul_f32_e32 v65, v9, v221
	v_mul_f32_e32 v42, v14, v210
	v_mul_f32_e32 v50, v14, v214
	v_mul_f32_e32 v58, v14, v218
	v_mul_f32_e32 v66, v14, v222
	v_mul_f32_e32 v43, v15, v211
	v_mul_f32_e32 v51, v15, v215
	v_mul_f32_e32 v59, v15, v219
	v_mul_f32_e32 v67, v15, v223
	v_fma_f32 v40, v10, v212, v40
	v_fma_f32 v48, v10, v216, v48
	v_fma_f32 v56, v10, v220, v56
	v_fma_f32 v64, v10, v224, v64
	v_fma_f32 v41, v11, v213, v41
	v_fma_f32 v49, v11, v217, v49
	v_fma_f32 v57, v11, v221, v57
	v_fma_f32 v65, v11, v225, v65
	v_fma_f32 v42, v16, v214, v42
	v_fma_f32 v50, v16, v218, v50
	v_fma_f32 v58, v16, v222, v58
	v_fma_f32 v66, v16, v226, v66
	v_fma_f32 v43, v17, v215, v43
	v_fma_f32 v51, v17, v219, v51
	v_fma_f32 v59, v17, v223, v59
	v_fma_f32 v67, v17, v227, v67
	v_fma_f32 v40, v12, v216, v40
	v_fma_f32 v48, v12, v220, v48
	v_fma_f32 v56, v12, v224, v56
	v_fma_f32 v64, v12, v228, v64
	v_fma_f32 v41, v13, v217, v41
	v_fma_f32 v49, v13, v221, v49
	v_fma_f32 v57, v13, v225, v57
	v_fma_f32 v65, v13, v229, v65
	v_fma_f32 v42, v18, v218, v42
	v_fma_f32 v50, v18, v222, v50
	v_fma_f32 v58, v18, v226, v58
	v_fma_f32 v66, v18, v230, v66
	v_fma_f32 v43, v19, v219, v43
	v_fma_f32 v51, v19, v223, v51
	v_fma_f32 v59, v19, v227, v59
	v_fma_f32 v67, v19, v231, v67
	v_mul_f32_e32 v44, 0xbfb8aa3b, v40
	v_mul_f32_e32 v52, 0xbfb8aa3b, v48
	v_mul_f32_e32 v60, 0xbfb8aa3b, v56
	v_mul_f32_e32 v68, 0xbfb8aa3b, v64
	v_mul_f32_e32 v45, 0xbfb8aa3b, v41
	v_mul_f32_e32 v53, 0xbfb8aa3b, v49
	v_mul_f32_e32 v61, 0xbfb8aa3b, v57
	v_mul_f32_e32 v69, 0xbfb8aa3b, v65
	v_exp_f32_e32 v44, v44
	v_exp_f32_e32 v52, v52
	v_exp_f32_e32 v60, v60
	v_exp_f32_e32 v68, v68
	v_exp_f32_e32 v45, v45
	v_exp_f32_e32 v53, v53
	v_exp_f32_e32 v61, v61
	v_exp_f32_e32 v69, v69
	v_add_f32_e32 v44, 1.0, v44
	v_add_f32_e32 v52, 1.0, v52
	v_add_f32_e32 v60, 1.0, v60
	v_add_f32_e32 v68, 1.0, v68
	v_add_f32_e32 v45, 1.0, v45
	v_add_f32_e32 v53, 1.0, v53
	v_add_f32_e32 v61, 1.0, v61
	v_add_f32_e32 v69, 1.0, v69
	v_rcp_f32_e32 v44, v44
	v_rcp_f32_e32 v52, v52
	v_rcp_f32_e32 v60, v60
	v_rcp_f32_e32 v68, v68
	v_rcp_f32_e32 v45, v45
	v_rcp_f32_e32 v53, v53
	v_rcp_f32_e32 v61, v61
	v_rcp_f32_e32 v69, v69
	v_mul_f32_e32 v40, v40, v44
	v_mul_f32_e32 v48, v48, v52
	v_mul_f32_e32 v56, v56, v60
	v_mul_f32_e32 v64, v64, v68
	v_mul_f32_e32 v41, v41, v45
	v_mul_f32_e32 v49, v49, v53
	v_mul_f32_e32 v57, v57, v61
	v_mul_f32_e32 v65, v65, v69
	v_mul_f32_e32 v40, v42, v40
	v_mul_f32_e32 v48, v50, v48
	v_mul_f32_e32 v56, v58, v56
	v_mul_f32_e32 v64, v66, v64
	v_mul_f32_e32 v41, v43, v41
	v_mul_f32_e32 v49, v51, v49
	v_mul_f32_e32 v57, v59, v57
	v_mul_f32_e32 v65, v67, v65
	v_cvt_pk_bf16_f32 v92, v40, v41
	v_cvt_pk_bf16_f32 v93, v48, v49
	v_cvt_pk_bf16_f32 v94, v56, v57
	v_cvt_pk_bf16_f32 v95, v64, v65
	s_and_b64 exec, exec, s[0:1]
	global_store_dword v126, v80, s[66:67]
	s_add_u32 s66, s66, 0x1600
	s_addc_u32 s67, s67, 0
	global_store_dword v126, v81, s[66:67]
	s_add_u32 s66, s66, 0x1600
	s_addc_u32 s67, s67, 0
	s_mov_b64 exec, s[70:71]
	global_store_dword v126, v82, s[66:67]
	s_add_u32 s66, s66, 0x1600
	s_addc_u32 s67, s67, 0
	global_store_dword v126, v83, s[66:67]
	s_add_u32 s66, s66, 0x1600
	s_addc_u32 s67, s67, 0
	global_store_dword v126, v84, s[66:67]
	s_add_u32 s66, s66, 0x1600
	s_addc_u32 s67, s67, 0
	global_store_dword v126, v85, s[66:67]
	s_add_u32 s66, s66, 0x1600
	s_addc_u32 s67, s67, 0
	global_store_dword v126, v86, s[66:67]
	s_add_u32 s66, s66, 0x1600
	s_addc_u32 s67, s67, 0
	global_store_dword v126, v87, s[66:67]
	s_add_u32 s66, s66, 0x1600
	s_addc_u32 s67, s67, 0
	global_store_dword v126, v88, s[66:67]
	s_add_u32 s66, s66, 0x1600
	s_addc_u32 s67, s67, 0
	global_store_dword v126, v89, s[66:67]
	s_add_u32 s66, s66, 0x1600
	s_addc_u32 s67, s67, 0
	global_store_dword v126, v90, s[66:67]
	s_add_u32 s66, s66, 0x1600
	s_addc_u32 s67, s67, 0
	global_store_dword v126, v91, s[66:67]
	s_add_u32 s66, s66, 0x1600
	s_addc_u32 s67, s67, 0
	global_store_dword v126, v92, s[66:67]
	s_add_u32 s66, s66, 0x1600
	s_addc_u32 s67, s67, 0
	global_store_dword v126, v93, s[66:67]
	s_add_u32 s66, s66, 0x1600
	s_addc_u32 s67, s67, 0
	global_store_dword v126, v94, s[66:67]
	s_add_u32 s66, s66, 0x1600
	s_addc_u32 s67, s67, 0
	global_store_dword v126, v95, s[66:67]
	s_branch .LBB0_851
